# speedup vs baseline: 1.0119x; 1.0065x over previous
; __device__ __forceinline__ void gemm_tile(const GemmArgs& ga, int wgid, int next_wgid, bool prefetched, u16* shm, unsigned char* ws, int wv_) {
;     ...
;     float sc[2][4][4];
;     _Pragma("unroll") for (int ai = 0; ai < 2; ++ai)
;       _Pragma("unroll") for (int m = 0; m < 4; ++m)
;         _Pragma("unroll") for (int j = 0; j < 4; ++j) sc[ai][m][j] = (epi == EPI_Z) ? e_ss[rbase + ai * HALF + m * 16 + j] : 0.f;
;     _Pragma("unroll") for (int ai = 0; ai < 2; ++ai)
;       _Pragma("unroll") for (int m = 0; m < 4; ++m)
;         _Pragma("unroll") for (int j = 0; j < 4; ++j) {
;           int row = rbase + ai * HALF + m * 16 + j;
;           float s = (epi == EPI_Z) ? rsqrtf(sc[ai][m][j] * (1.f / D_) + 1e-6f) : 1.f;
.LBB0_1084:
	v_ashrrev_i32_e32 v169, 31, v168
	v_lshl_add_u64 v[0:1], v[168:169], 2, s[68:69]
	v_mov_b32_e32 v0, v236
	v_fmamk_f32 v133, v0, 0x3a000000, v175

; __device__ __forceinline__ void gemm_tile(const GemmArgs& ga, int wgid, int next_wgid, bool prefetched, u16* shm, unsigned char* ws, int wv_) {
;     ...
;     float sc[2][4][4];
;     _Pragma("unroll") for (int ai = 0; ai < 2; ++ai)
;       _Pragma("unroll") for (int m = 0; m < 4; ++m)
;         _Pragma("unroll") for (int j = 0; j < 4; ++j) sc[ai][m][j] = (epi == EPI_Z) ? e_ss[rbase + ai * HALF + m * 16 + j] : 0.f;
;     _Pragma("unroll") for (int ai = 0; ai < 2; ++ai)
;       _Pragma("unroll") for (int m = 0; m < 4; ++m)
;         _Pragma("unroll") for (int j = 0; j < 4; ++j) {
;           int row = rbase + ai * HALF + m * 16 + j;
;           float s = (epi == EPI_Z) ? rsqrtf(sc[ai][m][j] * (1.f / D_) + 1e-6f) : 1.f;
.LBB0_1088:
	v_mov_b32_e32 v0, v238
	v_fmamk_f32 v131, v0, 0x3a000000, v175
.LBB0_1089:
	v_mov_b32_e32 v130, 0x358637bd
	s_and_b64 vcc, exec, s[6:7]
	v_readlane_b32 s2, v254, 51
	v_readlane_b32 s3, v254, 52
	s_cbranch_vccnz .LBB0_1091
	v_mov_b32_e32 v0, v239
	s_mov_b64 s[2:3], s[56:57]
	v_fmamk_f32 v130, v0, 0x3a000000, v175

; __device__ __forceinline__ void gemm_tile(const GemmArgs& ga, int wgid, int next_wgid, bool prefetched, u16* shm, unsigned char* ws, int wv_) {
;     ...
;     float sc[2][4][4];
;     _Pragma("unroll") for (int ai = 0; ai < 2; ++ai)
;       _Pragma("unroll") for (int m = 0; m < 4; ++m)
;         _Pragma("unroll") for (int j = 0; j < 4; ++j) sc[ai][m][j] = (epi == EPI_Z) ? e_ss[rbase + ai * HALF + m * 16 + j] : 0.f;
.LBB0_1097:
	v_ashrrev_i32_e32 v169, 31, v168
	v_lshl_add_u64 v[0:1], v[168:169], 2, s[68:69]
	global_load_dwordx4 v[208:211], v[0:1], off
	global_load_dwordx4 v[212:215], v[0:1], off offset:64
	global_load_dwordx4 v[216:219], v[0:1], off offset:128
	global_load_dwordx4 v[220:223], v[0:1], off offset:192
	global_load_dwordx4 v[224:227], v[0:1], off offset:512
	global_load_dwordx4 v[228:231], v[0:1], off offset:576
	global_load_dwordx4 v[232:235], v[0:1], off offset:640
	global_load_dwordx4 v[236:239], v[0:1], off offset:704
	s_waitcnt vmcnt(0)
	v_mov_b32_e32 v0, v208
	v_fmamk_f32 v172, v0, 0x3a000000, v175
	s_and_b64 vcc, exec, s[6:7]
	s_cbranch_vccnz .LBB0_1057
.LBB0_1098:
	v_ashrrev_i32_e32 v169, 31, v168
	v_lshl_add_u64 v[0:1], v[168:169], 2, s[68:69]
	v_mov_b32_e32 v0, v209
	v_fmamk_f32 v159, v0, 0x3a000000, v175
	v_mov_b32_e32 v165, 0x358637bd
	s_and_b64 vcc, exec, s[6:7]
	v_mov_b32_e32 v170, 0x358637bd
	s_cbranch_vccnz .LBB0_1058
.LBB0_1099:
	v_ashrrev_i32_e32 v169, 31, v168
	v_lshl_add_u64 v[0:1], v[168:169], 2, s[68:69]
	v_mov_b32_e32 v0, v210
	v_fmamk_f32 v170, v0, 0x3a000000, v175
	s_and_b64 vcc, exec, s[6:7]
	s_cbranch_vccnz .LBB0_1059
.LBB0_1100:
	v_ashrrev_i32_e32 v169, 31, v168
	v_lshl_add_u64 v[0:1], v[168:169], 2, s[68:69]
	v_mov_b32_e32 v0, v211
	v_fmamk_f32 v165, v0, 0x3a000000, v175
	v_mov_b32_e32 v163, 0x358637bd
	s_and_b64 vcc, exec, s[6:7]
	v_mov_b32_e32 v164, 0x358637bd
	s_cbranch_vccnz .LBB0_1060
.LBB0_1101:
	v_ashrrev_i32_e32 v169, 31, v168
	v_lshl_add_u64 v[0:1], v[168:169], 2, s[68:69]
	v_mov_b32_e32 v0, v212
	v_fmamk_f32 v164, v0, 0x3a000000, v175
	s_and_b64 vcc, exec, s[6:7]
	s_cbranch_vccnz .LBB0_1061
.LBB0_1102:
	v_ashrrev_i32_e32 v169, 31, v168
	v_lshl_add_u64 v[0:1], v[168:169], 2, s[68:69]
	v_mov_b32_e32 v0, v213
	v_fmamk_f32 v163, v0, 0x3a000000, v175
	v_mov_b32_e32 v160, 0x358637bd
	s_and_b64 vcc, exec, s[6:7]
	v_mov_b32_e32 v162, 0x358637bd
	s_cbranch_vccnz .LBB0_1062
.LBB0_1103:
	v_ashrrev_i32_e32 v169, 31, v168
	v_lshl_add_u64 v[0:1], v[168:169], 2, s[68:69]
	v_mov_b32_e32 v0, v214
	v_fmamk_f32 v162, v0, 0x3a000000, v175
	s_and_b64 vcc, exec, s[6:7]
	s_cbranch_vccnz .LBB0_1063
.LBB0_1104:
	v_ashrrev_i32_e32 v169, 31, v168
	v_lshl_add_u64 v[0:1], v[168:169], 2, s[68:69]
	v_mov_b32_e32 v0, v215
	v_fmamk_f32 v160, v0, 0x3a000000, v175
	v_mov_b32_e32 v157, 0x358637bd
	s_and_b64 vcc, exec, s[6:7]
	v_mov_b32_e32 v158, 0x358637bd
	s_cbranch_vccnz .LBB0_1064
.LBB0_1105:
	v_ashrrev_i32_e32 v169, 31, v168
	v_lshl_add_u64 v[0:1], v[168:169], 2, s[68:69]
	v_mov_b32_e32 v0, v216
	v_fmamk_f32 v158, v0, 0x3a000000, v175
	s_and_b64 vcc, exec, s[6:7]
	s_cbranch_vccnz .LBB0_1065
.LBB0_1106:
	v_ashrrev_i32_e32 v169, 31, v168
	v_lshl_add_u64 v[0:1], v[168:169], 2, s[68:69]
	v_mov_b32_e32 v0, v217
	v_fmamk_f32 v157, v0, 0x3a000000, v175
	v_mov_b32_e32 v155, 0x358637bd
	s_and_b64 vcc, exec, s[6:7]
	v_mov_b32_e32 v156, 0x358637bd
	s_cbranch_vccnz .LBB0_1066
.LBB0_1107:
	v_ashrrev_i32_e32 v169, 31, v168
	v_lshl_add_u64 v[0:1], v[168:169], 2, s[68:69]
	v_mov_b32_e32 v0, v218
	v_fmamk_f32 v156, v0, 0x3a000000, v175
	s_and_b64 vcc, exec, s[6:7]
	s_cbranch_vccnz .LBB0_1067
.LBB0_1108:
	v_ashrrev_i32_e32 v169, 31, v168
	v_lshl_add_u64 v[0:1], v[168:169], 2, s[68:69]
	v_mov_b32_e32 v0, v219
	v_fmamk_f32 v155, v0, 0x3a000000, v175
	v_mov_b32_e32 v152, 0x358637bd
	s_and_b64 vcc, exec, s[6:7]
	v_mov_b32_e32 v153, 0x358637bd
	s_cbranch_vccnz .LBB0_1068
.LBB0_1109:
	v_ashrrev_i32_e32 v169, 31, v168
	v_lshl_add_u64 v[0:1], v[168:169], 2, s[68:69]
	v_mov_b32_e32 v0, v220
	v_fmamk_f32 v153, v0, 0x3a000000, v175
	s_and_b64 vcc, exec, s[6:7]
	s_cbranch_vccnz .LBB0_1069
; __device__ __forceinline__ void gemm_tile(const GemmArgs& ga, int wgid, int next_wgid, bool prefetched, u16* shm, unsigned char* ws, int wv_) {
;     ...
;     float sc[2][4][4];
;     _Pragma("unroll") for (int ai = 0; ai < 2; ++ai)
;       _Pragma("unroll") for (int m = 0; m < 4; ++m)
;         _Pragma("unroll") for (int j = 0; j < 4; ++j) sc[ai][m][j] = (epi == EPI_Z) ? e_ss[rbase + ai * HALF + m * 16 + j] : 0.f;
.LBB0_1110:
	v_ashrrev_i32_e32 v169, 31, v168
	v_lshl_add_u64 v[0:1], v[168:169], 2, s[68:69]
	v_mov_b32_e32 v0, v221
	v_fmamk_f32 v152, v0, 0x3a000000, v175
	v_mov_b32_e32 v150, 0x358637bd
	s_and_b64 vcc, exec, s[6:7]
	v_mov_b32_e32 v151, 0x358637bd
	s_cbranch_vccnz .LBB0_1070
.LBB0_1111:
	v_ashrrev_i32_e32 v169, 31, v168
	v_lshl_add_u64 v[0:1], v[168:169], 2, s[68:69]
	v_mov_b32_e32 v0, v222
	v_fmamk_f32 v151, v0, 0x3a000000, v175
	s_and_b64 vcc, exec, s[6:7]
	s_cbranch_vccnz .LBB0_1071
.LBB0_1112:
	v_ashrrev_i32_e32 v169, 31, v168
	v_lshl_add_u64 v[0:1], v[168:169], 2, s[68:69]
	v_mov_b32_e32 v0, v223
	v_fmamk_f32 v150, v0, 0x3a000000, v175
	v_mov_b32_e32 v147, 0x358637bd
	s_and_b64 vcc, exec, s[6:7]
	v_mov_b32_e32 v149, 0x358637bd
	s_cbranch_vccnz .LBB0_1072
.LBB0_1113:
	v_ashrrev_i32_e32 v169, 31, v168
	v_lshl_add_u64 v[0:1], v[168:169], 2, s[68:69]
	v_mov_b32_e32 v0, v224
	v_fmamk_f32 v149, v0, 0x3a000000, v175
	s_and_b64 vcc, exec, s[6:7]
	s_cbranch_vccnz .LBB0_1073
.LBB0_1114:
	v_ashrrev_i32_e32 v169, 31, v168
	v_lshl_add_u64 v[0:1], v[168:169], 2, s[68:69]
	v_mov_b32_e32 v0, v225
	v_fmamk_f32 v147, v0, 0x3a000000, v175
	v_mov_b32_e32 v145, 0x358637bd
	s_and_b64 vcc, exec, s[6:7]
	v_mov_b32_e32 v146, 0x358637bd
	s_cbranch_vccnz .LBB0_1074
.LBB0_1115:
	v_ashrrev_i32_e32 v169, 31, v168
	v_lshl_add_u64 v[0:1], v[168:169], 2, s[68:69]
	v_mov_b32_e32 v0, v226
	v_fmamk_f32 v146, v0, 0x3a000000, v175
	s_and_b64 vcc, exec, s[6:7]
	s_cbranch_vccnz .LBB0_1075
.LBB0_1116:
	v_ashrrev_i32_e32 v169, 31, v168
	v_lshl_add_u64 v[0:1], v[168:169], 2, s[68:69]
	v_mov_b32_e32 v0, v227
	v_fmamk_f32 v145, v0, 0x3a000000, v175
	v_mov_b32_e32 v143, 0x358637bd
	s_and_b64 vcc, exec, s[6:7]
	v_mov_b32_e32 v144, 0x358637bd
	s_cbranch_vccnz .LBB0_1076
.LBB0_1117:
	v_ashrrev_i32_e32 v169, 31, v168
	v_lshl_add_u64 v[0:1], v[168:169], 2, s[68:69]
	v_mov_b32_e32 v0, v228
	v_fmamk_f32 v144, v0, 0x3a000000, v175
	s_and_b64 vcc, exec, s[6:7]
	s_cbranch_vccnz .LBB0_1077
.LBB0_1118:
	v_ashrrev_i32_e32 v169, 31, v168
	v_lshl_add_u64 v[0:1], v[168:169], 2, s[68:69]
	v_mov_b32_e32 v0, v229
	v_fmamk_f32 v143, v0, 0x3a000000, v175
	v_mov_b32_e32 v140, 0x358637bd
	s_and_b64 vcc, exec, s[6:7]
	v_mov_b32_e32 v141, 0x358637bd
	s_cbranch_vccnz .LBB0_1078
.LBB0_1119:
	v_ashrrev_i32_e32 v169, 31, v168
	v_lshl_add_u64 v[0:1], v[168:169], 2, s[68:69]
	v_mov_b32_e32 v0, v230
	v_fmamk_f32 v141, v0, 0x3a000000, v175
	s_and_b64 vcc, exec, s[6:7]
	s_cbranch_vccnz .LBB0_1079
.LBB0_1120:
	v_ashrrev_i32_e32 v169, 31, v168
	v_lshl_add_u64 v[0:1], v[168:169], 2, s[68:69]
	v_mov_b32_e32 v0, v231
	v_fmamk_f32 v140, v0, 0x3a000000, v175
	v_mov_b32_e32 v138, 0x358637bd
	s_and_b64 vcc, exec, s[6:7]
	v_mov_b32_e32 v139, 0x358637bd
	s_cbranch_vccnz .LBB0_1080
.LBB0_1121:
	v_ashrrev_i32_e32 v169, 31, v168
	v_lshl_add_u64 v[0:1], v[168:169], 2, s[68:69]
	v_mov_b32_e32 v0, v232
	v_fmamk_f32 v139, v0, 0x3a000000, v175
	s_and_b64 vcc, exec, s[6:7]
	s_cbranch_vccnz .LBB0_1081
.LBB0_1122:
	v_ashrrev_i32_e32 v169, 31, v168
	v_lshl_add_u64 v[0:1], v[168:169], 2, s[68:69]
	v_mov_b32_e32 v0, v233
	v_fmamk_f32 v138, v0, 0x3a000000, v175
	v_mov_b32_e32 v135, 0x358637bd
	s_and_b64 vcc, exec, s[6:7]
	v_mov_b32_e32 v137, 0x358637bd
	s_cbranch_vccnz .LBB0_1082
.LBB0_1123:
	v_ashrrev_i32_e32 v169, 31, v168
	v_lshl_add_u64 v[0:1], v[168:169], 2, s[68:69]
	v_mov_b32_e32 v0, v234
	v_fmamk_f32 v137, v0, 0x3a000000, v175
	s_and_b64 vcc, exec, s[6:7]
	s_cbranch_vccnz .LBB0_1083
.LBB0_1124:
	v_ashrrev_i32_e32 v169, 31, v168
	v_lshl_add_u64 v[0:1], v[168:169], 2, s[68:69]
	v_mov_b32_e32 v0, v235
	v_fmamk_f32 v135, v0, 0x3a000000, v175
	s_and_b64 vcc, exec, s[6:7]
	v_mov_b32_e32 v133, 0x358637bd
	s_cbranch_vccz .LBB0_1084
	s_branch .LBB0_1085

; __device__ __forceinline__ void gemm_tile(const GemmArgs& ga, int wgid, int next_wgid, bool prefetched, u16* shm, unsigned char* ws, int wv_) {
;     ...
;     float sc[2][4][4];
;     _Pragma("unroll") for (int ai = 0; ai < 2; ++ai)
;       _Pragma("unroll") for (int m = 0; m < 4; ++m)
;         _Pragma("unroll") for (int j = 0; j < 4; ++j) sc[ai][m][j] = (epi == EPI_Z) ? e_ss[rbase + ai * HALF + m * 16 + j] : 0.f;
.LBB0_1126:
	v_ashrrev_i32_e32 v169, 31, v168
	v_lshl_add_u64 v[0:1], v[168:169], 2, s[68:69]
	v_mov_b32_e32 v0, v237
	v_fmamk_f32 v132, v0, 0x3a000000, v175
	s_and_b64 vcc, exec, s[6:7]
	v_lshl_add_u64 v[128:129], v[168:169], 2, s[68:69]
	s_cbranch_vccz .LBB0_1088
	s_branch .LBB0_1089
